# role alternation in phase +5: WG blocks with unit-index bit 4 set run post before RG-LRU (memory-bound and VALU-bound sections overlap chip-wide), on top of ST2
# baseline (speedup 1.0000x reference)
; #define LAS __attribute__((address_space(3)))
; #define SUB(k, bit) (!(kargs()->li == 1 && (k) == lo) || ((kargs()->submask >> (bit)) & 1u))
; __global__ void __launch_bounds__(NWAVES * 64, 2) fwd(Args args_unused) {
;     ...
;         if (IN(pb + 5)) {
;             PH_PTRS PH_LAYER
;             if (SUB(pb + 5, 0)) {
;                 constexpr int LT = 136, AS = 68;
;                 LAS bf16* Xs = (LAS bf16*)lds;
;                 LAS bf16* Ws = Xs + 128 * LT;
;                 LAS float* As = (LAS float*)(Ws + 128 * LT);
;                 LAS float* Us = As + 128 * AS;
;                 LAS float* sP = Us + 128 * AS;
;                 LAS float* sH = sP + 512;
;                 LAS float* cS = sH + 512;
;                 LAS float* cst = cS + 128;
;                 static_assert(2 * 128 * LT * 2 + (2 * 128 * AS + 512 + 512 + 128 + 192) * 4 <= LDSCTL_OFF, "LRU LDS map");
;                 const int qq = lane & 15, q4 = lane >> 4, w = wave;
;                 for (int un = vcu; un < 256; un += G) {
;                     const int b = un >> 4, j = (un >> 1) & 7, h2 = un & 1, chb = j * 128 + 64 * h2;
;                     __syncthreads();
;                     { const bf16* wg = (const bf16*)(wl + WL_G);
; #pragma unroll
;                       for (int k = 0; k < 4; ++k) { const int idx = tid + 512 * k, n = idx >> 4, part = idx & 15; const int srow = j * 256 + (n < 64 ? 64 * h2 + n : 128 + 64 * h2 + (n - 64));
;                           *(LAS v4u*)(Ws + n * LT + part * 8) = *(const v4u*)(wg + (size_t)srow * 128 + part * 8); }
;                       if (tid < 64) { cst[tid] = A->in[I_BR][l * DM + chb + tid]; cst[64 + tid] = A->in[I_BI][l * DM + chb + tid]; cst[128 + tid] = ((const float*)(ws + WS_SPL))[l * DM + chb + tid]; cS[tid] = 0.f; } }
;                     const int cpart = tid & 15, ctb = 4 * (tid >> 4);
;                     float cwv[4][8], cbv[8];
; #pragma unroll
;                     for (int e = 0; e < 8; ++e) { cbv[e] = A->in[I_CCB][l * DM + j * 128 + cpart * 8 + e];
; #pragma unroll
;                         for (int jj = 0; jj < 4; ++jj) cwv[jj][e] = A->in[I_CCW][(size_t)(l * 4 + jj) * DM + j * 128 + cpart * 8 + e]; }
;                     v4u xr[7] = {(v4u){0u, 0u, 0u, 0u}, (v4u){0u, 0u, 0u, 0u}, (v4u){0u, 0u, 0u, 0u}, (v4u){0u, 0u, 0u, 0u}, (v4u){0u, 0u, 0u, 0u}, (v4u){0u, 0u, 0u, 0u}, (v4u){0u, 0u, 0u, 0u}};
;     ...
;                     LRU_LOAD(0);
.LBB0_1808:
	v_readlane_b32 s99, v254, 3
	s_nop 3
	s_bfe_u32 s99, s99, 0x10004
	s_cmp_eq_u32 s99, 1
	s_cselect_b32 s98, 0, 2
.Lro_again_0:
	s_cmp_lt_i32 s84, 9
	s_cselect_b64 s[4:5], -1, 0
	s_and_b64 s[0:1], s[4:5], s[0:1]
	s_andn2_b64 vcc, exec, s[0:1]
	s_cbranch_vccnz .LBB0_1930
	s_mov_b64 s[34:35], s[82:83]
	s_load_dwordx4 s[28:31], s[34:35], 0x140
	s_mov_b32 s6, 0
	s_load_dword s3, s[82:83], 0x168
	v_readlane_b32 s33, v254, 3
	s_mov_b32 s63, s2
	v_mov_b32_e32 v126, v0
	s_waitcnt lgkmcnt(0)
	s_add_u32 s26, s30, 0x1d200000
	s_addc_u32 s27, s31, 0
	v_ashrrev_i32_e32 v144, 6, v126
	s_mov_b32 s41, 0
	v_and_b32_e32 v1, 63, v126
	s_cmpk_gt_i32 s33, 0xff
	v_readfirstlane_b32 s62, v144
	s_cselect_b32 s99, 1, 0
	s_cmp_eq_u32 s98, 0
	s_cbranch_scc1 .Lp8_post_0
	s_cmp_lg_u32 s99, 0
	s_cbranch_scc1 .LBB0_1918
	v_lshlrev_b32_e32 v2, 4, v126
	v_and_b32_e32 v4, 0xf0, v2
	v_mov_b32_e32 v2, 0
	v_and_b32_e32 v3, 15, v126
	v_mov_b32_e32 v5, v2
	v_lshlrev_b32_e32 v8, 3, v126
	v_lshl_add_u64 v[6:7], s[30:31], 0, v[4:5]
	s_mov_b64 s[4:5], 0x4300000
	v_lshl_or_b32 v5, s62, 4, v3
	s_movk_i32 s47, 0x110
	s_add_i32 s7, s6, 0x22000
	s_add_i32 s40, s6, 0x22800
	s_add_i32 s64, s6, 0x23000
	s_add_i32 s44, s6, 0x23200
	v_lshl_add_u64 v[128:129], v[6:7], 0, s[4:5]
	v_add_u32_e32 v6, s6, v4
	v_lshlrev_b32_e32 v4, 2, v126
	v_and_b32_e32 v150, 56, v8
	v_mul_lo_u32 v8, v5, s47
	v_lshrrev_b32_e32 v5, 2, v126
	v_add_u32_e32 v145, s44, v4
	v_add_u32_e32 v146, s64, v4
	v_and_b32_e32 v13, 12, v5
	v_add_u32_e32 v153, s7, v4
	v_add_u32_e32 v154, s40, v4
	v_lshlrev_b32_e32 v4, 1, v150
	v_mov_b32_e32 v5, v2
	v_lshl_add_u64 v[4:5], s[30:31], 0, v[4:5]
	s_mov_b64 s[10:11], 0x79f00000
	s_add_i32 s45, s6, 0x19800
	s_add_i32 s46, s6, 0x11000
	v_lshl_add_u64 v[132:133], v[4:5], 0, s[10:11]
	v_add_u32_e32 v5, 0x200, v126
	s_add_u32 s42, s30, 0xb080000
	v_ashrrev_i32_e32 v156, 4, v5
	v_ashrrev_i32_e32 v136, 3, v5
	v_lshlrev_b32_e32 v5, 2, v13
	s_addc_u32 s43, s31, 0
	v_add_u32_e32 v151, s6, v8
	s_add_i32 s48, s6, 0x23300
	s_add_i32 s49, s6, 0x23400
	v_add3_u32 v162, s46, v8, v5
	v_add3_u32 v163, s45, v8, v5
	v_or_b32_e32 v8, 64, v5
	v_add_u32_e32 v159, s44, v5
	v_add_u32_e32 v160, s48, v5
	v_add_u32_e32 v161, s49, v5
	v_add_u32_e32 v164, s44, v8
	v_add_u32_e32 v165, s48, v8
	v_add_u32_e32 v166, s49, v8
	v_or_b32_e32 v8, 0x80, v5
	v_or_b32_e32 v5, 0xc0, v5
	v_add_u32_e32 v167, s44, v8
	v_add_u32_e32 v170, s44, v5
	s_movk_i32 s44, 0x440
	v_add_u32_e32 v171, s48, v5
	v_add_u32_e32 v172, s49, v5
	v_mul_lo_u32 v5, v144, s44
	v_or_b32_e32 v5, v5, v1
	v_lshlrev_b32_e32 v5, 2, v5
	v_add_u32_e32 v173, s46, v5
	v_add_u32_e32 v174, s45, v5
	v_lshl_or_b32 v5, v144, 4, 1
	s_movk_i32 s44, 0x44
	v_add_u32_e32 v168, s48, v8
	v_add_u32_e32 v169, s49, v8
	v_mul_lo_u32 v8, v5, s44
	v_lshlrev_b32_e32 v10, 2, v1
	v_add_u32_e32 v19, v8, v1
	v_add_u32_e32 v14, s45, v10
	v_lshl_add_u32 v175, v19, 2, s46
	v_add_u32_e32 v19, 0x44, v8
	v_add_u32_e32 v20, v19, v1
	v_lshl_add_u32 v178, v19, 2, v14
	v_add_u32_e32 v19, 0x88, v8
	v_lshl_add_u32 v177, v20, 2, s46
	v_add_u32_e32 v20, v19, v1
	v_lshl_add_u32 v180, v19, 2, v14
	v_add_u32_e32 v19, 0xcc, v8
	v_lshl_add_u32 v179, v20, 2, s46
	v_add_u32_e32 v20, v19, v1
	v_lshl_add_u32 v182, v19, 2, v14
	v_add_u32_e32 v19, 0x110, v8
	v_lshl_add_u32 v181, v20, 2, s46
	v_add_u32_e32 v20, v19, v1
	v_lshl_add_u32 v184, v19, 2, v14
	v_add_u32_e32 v19, 0x154, v8
	v_lshl_add_u32 v183, v20, 2, s46
	v_add_u32_e32 v20, v19, v1
	v_lshl_add_u32 v186, v19, 2, v14
	v_add_u32_e32 v19, 0x198, v8
	v_lshl_add_u32 v185, v20, 2, s46
	v_add_u32_e32 v20, v19, v1
	v_lshl_add_u32 v188, v19, 2, v14
	v_add_u32_e32 v19, 0x1dc, v8
	v_lshl_add_u32 v187, v20, 2, s46
	v_add_u32_e32 v20, v19, v1
	v_lshl_add_u32 v190, v19, 2, v14
	v_add_u32_e32 v19, 0x220, v8
	v_lshl_add_u32 v189, v20, 2, s46
	v_add_u32_e32 v20, v19, v1
	v_lshl_add_u32 v192, v19, 2, v14
	v_add_u32_e32 v19, 0x264, v8
	v_lshl_add_u32 v191, v20, 2, s46
	v_add_u32_e32 v20, v19, v1
	v_lshl_add_u32 v194, v19, 2, v14
	v_add_u32_e32 v19, 0x2a8, v8
	v_lshl_add_u32 v193, v20, 2, s46
	v_add_u32_e32 v20, v19, v1
	v_lshl_add_u32 v196, v19, 2, v14
	v_add_u32_e32 v19, 0x2ec, v8
	s_load_dwordx4 s[36:39], s[34:35], 0xd8
	v_lshl_add_u32 v195, v20, 2, s46
	v_add_u32_e32 v20, v19, v1
	v_lshl_add_u32 v198, v19, 2, v14
	v_add_u32_e32 v19, 0x330, v8
	v_ashrrev_i32_e32 v7, 2, v126
	v_add_u32_e32 v17, 0x400, v126
	v_add_u32_e32 v18, 0x600, v126
	v_lshl_add_u32 v176, v8, 2, v14
	v_lshl_add_u32 v197, v20, 2, s46
	v_add_u32_e32 v20, v19, v1
	v_lshl_add_u32 v200, v19, 2, v14
	v_add_u32_e32 v19, 0x374, v8
	v_add_u32_e32 v8, 0x3b8, v8
	v_and_b32_e32 v9, -4, v7
	v_and_b32_e32 v152, 48, v126
	v_ashrrev_i32_e32 v155, 4, v126
	v_ashrrev_i32_e32 v157, 4, v17
	v_ashrrev_i32_e32 v158, 4, v18
	v_cmp_lt_i32_e64 s[18:19], 3, v7
	v_cmp_lt_i32_e64 s[20:21], -1, v7
	v_or_b32_e32 v7, 3, v7
	v_ashrrev_i32_e32 v134, 3, v126
	v_lshl_add_u32 v199, v20, 2, s46
	v_add_u32_e32 v20, v19, v1
	v_lshl_add_u32 v202, v19, 2, v14
	v_add_u32_e32 v19, v8, v1
	s_movk_i32 s44, 0x1100
	v_lshlrev_b32_e32 v147, 3, v3
	v_add_u32_e32 v130, -3, v9
	v_lshl_add_u32 v11, v3, 4, s6
	v_add_u32_e32 v149, 0x7d, v9
	v_add_u32_e32 v12, s6, v152
	v_lshl_add_u32 v15, v150, 2, s45
	v_mul_lo_u32 v4, v155, s47
	v_mul_lo_u32 v16, v156, s47
	v_mul_lo_u32 v17, v157, s47
	v_mul_lo_u32 v18, v158, s47
	v_cmp_lt_i32_e64 s[22:23], -2, v9
	v_cmp_lt_i32_e64 s[24:25], -3, v9
	v_mul_lo_u32 v9, v9, s47
	v_mul_lo_u32 v7, v7, s47
	v_mul_u32_u24_e32 v3, 0x110, v3
	v_lshl_add_u32 v201, v20, 2, s46
	v_lshl_add_u32 v203, v19, 2, s46
	v_lshl_add_u32 v204, v8, 2, v14
	v_mul_lo_u32 v8, v144, s44
	v_mul_lo_u32 v5, v5, s47
	v_mul_lo_u32 v19, v134, s47
	v_mul_lo_u32 v20, v136, s47
	v_cmp_gt_i32_e64 s[4:5], 64, v126
	v_ashrrev_i32_e32 v131, 31, v130
	v_add_u32_e32 v148, s64, v10
	v_cmp_lt_i32_e64 s[6:7], 0, v144
	v_cmp_eq_u32_e64 s[8:9], 7, v144
	v_ashrrev_i32_e32 v127, 31, v126
	v_cmp_gt_i32_e64 s[10:11], 64, v155
	v_cmp_gt_i32_e64 s[12:13], 64, v156
	v_cmp_gt_i32_e64 s[14:15], 64, v157
	v_cmp_gt_i32_e64 s[16:17], 64, v158
	v_ashrrev_i32_e32 v135, 31, v134
	v_ashrrev_i32_e32 v137, 31, v136
	v_lshl_add_u32 v205, v13, 1, v151
	v_add_u32_e32 v206, s40, v10
	v_add_u32_e32 v207, v6, v4
	v_add_u32_e32 v208, v6, v16
	v_add_u32_e32 v209, v6, v17
	v_add_u32_e32 v210, v6, v18
	s_mov_b64 s[44:45], 0x1000
	s_mov_b64 s[46:47], 0x2000
	s_mov_b64 s[48:49], 0x3000
	v_add_u32_e32 v211, v11, v9
	v_add_u32_e32 v212, v11, v7
	v_add_u32_e32 v213, v12, v3
	s_mov_b32 s65, 0xbecccccd
	v_mov_b32_e32 v214, 0x3c088889
	v_add_u32_e32 v215, v14, v8
	v_add_u32_e32 v216, v14, v5
	v_add_u32_e32 v217, v15, v19
	v_add_u32_e32 v218, v15, v20
	s_mov_b32 s66, s33
	s_branch .LBB0_1812

; #define SUB(k, bit) (!(kargs()->li == 1 && (k) == lo) || ((kargs()->submask >> (bit)) & 1u))
; __global__ void __launch_bounds__(NWAVES * 64, 2) fwd(Args args_unused) {
;     ...
;             if (SUB(pb + 5, 1)) {
; #pragma unroll
;                 for (int q = 0; q < 2; ++q) { const f32x4 ga_ = *(const f32x4*)(A->in[I_GSSM] + l * DM + q * 512 + 8 * lane), gb_ = *(const f32x4*)(A->in[I_GSSM] + l * DM + q * 512 + 8 * lane + 4);
;                     gnv[q][0] = ga_.x; gnv[q][1] = ga_.y; gnv[q][2] = ga_.z; gnv[q][3] = ga_.w; gnv[q][4] = gb_.x; gnv[q][5] = gb_.y; gnv[q][6] = gb_.z; gnv[q][7] = gb_.w; } }
;             if (SUB(pb + 5, 1))
;             for (int row0 = gw; row0 < M; row0 += 2 * NGW) {
;                 const int hh = lane >> 3;
;                 float l0[2], l1[2], l2[2]; v4u r0[2], r1[2], r2[2], yr[2][2], zr[2][2];
; #pragma unroll
;                 for (int k = 0; k < 2; ++k) { const int row = row0 + k * NGW;
;                     l0[k] = 0.f; l1[k] = 0.f; l2[k] = 0.f; r0[k] = (v4u){0u, 0u, 0u, 0u}; r1[k] = (v4u){0u, 0u, 0u, 0u}; r2[k] = (v4u){0u, 0u, 0u, 0u};
; #pragma unroll
;                     for (int q = 0; q < 2; ++q) { yr[k][q] = (v4u){0u, 0u, 0u, 0u}; zr[k][q] = (v4u){0u, 0u, 0u, 0u}; }
;                     if (row < M) {
;                         l0[k] = LSE[((size_t)0 * M + row) * 8 + hh]; l1[k] = LSE[((size_t)1 * M + row) * 8 + hh]; l2[k] = LSE[((size_t)2 * M + row) * 8 + hh];
;                         r0[k] = *(const v4u*)(OG + ((size_t)0 * M + row) * 512 + 8 * lane); r1[k] = *(const v4u*)(OG + ((size_t)1 * M + row) * 512 + 8 * lane); r2[k] = *(const v4u*)(OG + ((size_t)2 * M + row) * 512 + 8 * lane);
; #pragma unroll
;                         for (int q = 0; q < 2; ++q) { const int col = q * 512 + 8 * lane; yr[k][q] = *(const v4u*)(YS + (size_t)row * DM + col); zr[k][q] = *(const v4u*)ZP(Z, row, ZZB + col); } } }
.Lp8_post_0:
	s_cmp_eq_u32 s98, 1
	s_cbranch_scc1 .Lro_fin_0
	s_lshl_b32 s4, s33, 3
	s_add_i32 s4, s4, s62
	s_cmp_lt_i32 s4, 0x8100
	s_mov_b32 s5, 0x8100
	s_cbranch_scc0 .LBB0_1930
	s_load_dwordx2 s[6:7], s[34:35], 0xc8
	v_lshlrev_b32_e32 v18, 5, v1
	v_mov_b32_e32 v75, 0
	v_mov_b32_e32 v20, 0x91200
	s_lshl_b32 s12, s3, 3
	s_waitcnt lgkmcnt(0)
	global_load_dwordx4 v[2:5], v18, s[6:7]
	global_load_dwordx4 v[6:9], v18, s[6:7] offset:16
	global_load_dwordx4 v[10:13], v18, s[6:7] offset:2048
	global_load_dwordx4 v[14:17], v18, s[6:7] offset:2064
	v_lshrrev_b32_e32 v18, 1, v1
	v_and_b32_e32 v74, 28, v18
	v_lshl_add_u64 v[18:19], s[30:31], 0, v[74:75]
	s_mov_b64 s[6:7], 0xb800000
	v_lshlrev_b32_e32 v74, 4, v1
	v_lshl_add_u64 v[76:77], v[18:19], 0, s[6:7]
	v_lshl_add_u64 v[18:19], s[30:31], 0, v[74:75]
	s_mov_b64 s[6:7], 0x67c00000
	v_lshl_add_u64 v[78:79], v[18:19], 0, s[6:7]
	v_and_b32_e32 v74, 0x1f0, v74
	s_mov_b64 s[6:7], 0x75e00000
	v_lshrrev_b32_e32 v1, 5, v1
	v_lshl_add_u64 v[80:81], s[26:27], 0, v[74:75]
	v_lshl_add_u64 v[82:83], v[18:19], 0, s[6:7]
	v_mad_u32_u24 v74, v1, s5, v20
	v_mov_b32_e32 v20, 0xa1400
	s_mov_b64 s[6:7], 0x6dd00000
	v_mad_u32_u24 v84, v1, s5, v20
	v_lshl_add_u64 v[86:87], v[18:19], 0, s[6:7]
	s_mov_b64 s[6:7], 0x5fb00000
	v_mbcnt_lo_u32_b32 v1, -1, 0
	v_mov_b32_e32 v85, v75
	v_lshl_add_u64 v[88:89], v[18:19], 0, s[6:7]
	s_lshl_b32 s3, s3, 4
	v_mbcnt_hi_u32_b32 v1, -1, v1
	v_mov_b32_e32 v90, 0x358637bd
	s_branch .LBB0_1926

; #define SEAM(k) do { if (IN(k) && IN((k) + 1)) { KArgs Ab = kargs(); XcdBarrier bar_; bar_.bar = (unsigned*)(Ab->ws + WS_CTL) + CW_BAR + Ab->li * XCD_BAR_WORDS; bar_.x = xb_xcc_id(); bar_.st = MISC + 8; xcd_barrier(bar_, (int)threadIdx.x); } } while (0)
; __global__ void __launch_bounds__(NWAVES * 64, 2) fwd(Args args_unused) {
;     ...
;             }
;         }
;         SEAM(pb + 5);
.LBB0_1930:
	s_cmp_lg_u32 s98, 0
	s_cbranch_scc1 .Lro_fin_0
	s_mov_b32 s98, 1
	s_branch .Lro_again_0

; #define LAS __attribute__((address_space(3)))
; #define SUB(k, bit) (!(kargs()->li == 1 && (k) == lo) || ((kargs()->submask >> (bit)) & 1u))
; __global__ void __launch_bounds__(NWAVES * 64, 2) fwd(Args args_unused) {
;     ...
;         if (IN(pb + 5)) {
;             PH_PTRS PH_LAYER
;             if (SUB(pb + 5, 0)) {
;                 constexpr int LT = 136, AS = 68;
;                 LAS bf16* Xs = (LAS bf16*)lds;
;                 LAS bf16* Ws = Xs + 128 * LT;
;                 LAS float* As = (LAS float*)(Ws + 128 * LT);
;                 LAS float* Us = As + 128 * AS;
;                 LAS float* sP = Us + 128 * AS;
;                 LAS float* sH = sP + 512;
;                 LAS float* cS = sH + 512;
;                 LAS float* cst = cS + 128;
;                 static_assert(2 * 128 * LT * 2 + (2 * 128 * AS + 512 + 512 + 128 + 192) * 4 <= LDSCTL_OFF, "LRU LDS map");
;                 const int qq = lane & 15, q4 = lane >> 4, w = wave;
;                 for (int un = vcu; un < 256; un += G) {
;                     const int b = un >> 4, j = (un >> 1) & 7, h2 = un & 1, chb = j * 128 + 64 * h2;
;                     __syncthreads();
;                     { const bf16* wg = (const bf16*)(wl + WL_G);
; #pragma unroll
;                       for (int k = 0; k < 4; ++k) { const int idx = tid + 512 * k, n = idx >> 4, part = idx & 15; const int srow = j * 256 + (n < 64 ? 64 * h2 + n : 128 + 64 * h2 + (n - 64));
;                           *(LAS v4u*)(Ws + n * LT + part * 8) = *(const v4u*)(wg + (size_t)srow * 128 + part * 8); }
;                       if (tid < 64) { cst[tid] = A->in[I_BR][l * DM + chb + tid]; cst[64 + tid] = A->in[I_BI][l * DM + chb + tid]; cst[128 + tid] = ((const float*)(ws + WS_SPL))[l * DM + chb + tid]; cS[tid] = 0.f; } }
;                     const int cpart = tid & 15, ctb = 4 * (tid >> 4);
;                     float cwv[4][8], cbv[8];
; #pragma unroll
;                     for (int e = 0; e < 8; ++e) { cbv[e] = A->in[I_CCB][l * DM + j * 128 + cpart * 8 + e];
; #pragma unroll
;                         for (int jj = 0; jj < 4; ++jj) cwv[jj][e] = A->in[I_CCW][(size_t)(l * 4 + jj) * DM + j * 128 + cpart * 8 + e]; }
;                     v4u xr[7] = {(v4u){0u, 0u, 0u, 0u}, (v4u){0u, 0u, 0u, 0u}, (v4u){0u, 0u, 0u, 0u}, (v4u){0u, 0u, 0u, 0u}, (v4u){0u, 0u, 0u, 0u}, (v4u){0u, 0u, 0u, 0u}, (v4u){0u, 0u, 0u, 0u}};
;     ...
;                     LRU_LOAD(0);
.Lro_again_1:
	s_cmp_lt_i32 s84, 19
	s_cselect_b64 s[4:5], -1, 0
	s_and_b64 s[0:1], s[4:5], s[0:1]
	s_andn2_b64 vcc, exec, s[0:1]
	s_cbranch_vccnz .LBB0_3954
	s_mov_b64 s[34:35], s[82:83]
	s_load_dwordx4 s[28:31], s[34:35], 0x140
	s_mov_b32 s6, 0
	s_mov_b32 s63, s2
	s_load_dword s3, s[82:83], 0x168
	v_readlane_b32 s33, v254, 3
	v_mov_b32_e32 v126, v0
	s_waitcnt lgkmcnt(0)
	s_add_u32 s26, s30, 0x1d200000
	s_addc_u32 s27, s31, 0
	v_ashrrev_i32_e32 v144, 6, v126
	s_mov_b32 s41, 0
	v_and_b32_e32 v1, 63, v126
	s_cmpk_gt_i32 s33, 0xff
	v_readfirstlane_b32 s62, v144
	s_cselect_b32 s99, 1, 0
	s_cmp_eq_u32 s98, 0
	s_cbranch_scc1 .Lp8_post_1
	s_cmp_lg_u32 s99, 0
	s_cbranch_scc1 .LBB0_3942
	v_lshlrev_b32_e32 v2, 4, v126
	v_and_b32_e32 v4, 0xf0, v2
	v_mov_b32_e32 v2, 0
	v_and_b32_e32 v3, 15, v126
	v_mov_b32_e32 v5, v2
	v_lshlrev_b32_e32 v8, 3, v126
	v_lshl_add_u64 v[6:7], s[30:31], 0, v[4:5]
	s_mov_b64 s[4:5], 0x8800000
	v_lshl_or_b32 v5, s62, 4, v3
	s_movk_i32 s47, 0x110
	s_add_i32 s7, s6, 0x22000
	s_add_i32 s40, s6, 0x22800
	s_add_i32 s64, s6, 0x23000
	s_add_i32 s44, s6, 0x23200
	v_lshl_add_u64 v[128:129], v[6:7], 0, s[4:5]
	v_add_u32_e32 v6, s6, v4
	v_lshlrev_b32_e32 v4, 2, v126
	v_and_b32_e32 v153, 56, v8
	v_mul_lo_u32 v8, v5, s47
	v_lshrrev_b32_e32 v5, 2, v126
	v_add_u32_e32 v146, s44, v4
	v_add_u32_e32 v147, s64, v4
	v_and_b32_e32 v13, 12, v5
	v_add_u32_e32 v156, s7, v4
	v_add_u32_e32 v157, s40, v4
	v_lshlrev_b32_e32 v4, 1, v153
	v_mov_b32_e32 v5, v2
	v_lshl_add_u64 v[4:5], s[30:31], 0, v[4:5]
	s_mov_b64 s[10:11], 0x79f00000
	s_add_i32 s45, s6, 0x19800
	s_add_i32 s46, s6, 0x11000
	v_lshl_add_u64 v[132:133], v[4:5], 0, s[10:11]
	v_add_u32_e32 v5, 0x200, v126
	s_add_u32 s42, s30, 0xb080000
	v_ashrrev_i32_e32 v159, 4, v5
	v_ashrrev_i32_e32 v136, 3, v5
	v_lshlrev_b32_e32 v5, 2, v13
	s_addc_u32 s43, s31, 0
	v_add_u32_e32 v154, s6, v8
	s_add_i32 s48, s6, 0x23300
	s_add_i32 s49, s6, 0x23400
	v_add3_u32 v165, s46, v8, v5
	v_add3_u32 v166, s45, v8, v5
	v_or_b32_e32 v8, 64, v5
	v_add_u32_e32 v162, s44, v5
	v_add_u32_e32 v163, s48, v5
	v_add_u32_e32 v164, s49, v5
	v_add_u32_e32 v167, s44, v8
	v_add_u32_e32 v168, s48, v8
	v_add_u32_e32 v169, s49, v8
	v_or_b32_e32 v8, 0x80, v5
	v_or_b32_e32 v5, 0xc0, v5
	v_add_u32_e32 v170, s44, v8
	v_add_u32_e32 v173, s44, v5
	s_movk_i32 s44, 0x440
	v_add_u32_e32 v174, s48, v5
	v_add_u32_e32 v175, s49, v5
	v_mul_lo_u32 v5, v144, s44
	v_or_b32_e32 v5, v5, v1
	v_lshlrev_b32_e32 v5, 2, v5
	v_add_u32_e32 v176, s46, v5
	v_add_u32_e32 v177, s45, v5
	v_lshl_or_b32 v5, v144, 4, 1
	s_movk_i32 s44, 0x44
	v_add_u32_e32 v171, s48, v8
	v_add_u32_e32 v172, s49, v8
	v_mul_lo_u32 v8, v5, s44
	v_lshlrev_b32_e32 v10, 2, v1
	v_add_u32_e32 v19, v8, v1
	v_add_u32_e32 v14, s45, v10
	v_lshl_add_u32 v178, v19, 2, s46
	v_add_u32_e32 v19, 0x44, v8
	v_add_u32_e32 v20, v19, v1
	v_lshl_add_u32 v181, v19, 2, v14
	v_add_u32_e32 v19, 0x88, v8
	v_lshl_add_u32 v180, v20, 2, s46
	v_add_u32_e32 v20, v19, v1
	v_lshl_add_u32 v183, v19, 2, v14
	v_add_u32_e32 v19, 0xcc, v8
	v_lshl_add_u32 v182, v20, 2, s46
	v_add_u32_e32 v20, v19, v1
	v_lshl_add_u32 v185, v19, 2, v14
	v_add_u32_e32 v19, 0x110, v8
	v_lshl_add_u32 v184, v20, 2, s46
	v_add_u32_e32 v20, v19, v1
	v_lshl_add_u32 v187, v19, 2, v14
	v_add_u32_e32 v19, 0x154, v8
	v_lshl_add_u32 v186, v20, 2, s46
	v_add_u32_e32 v20, v19, v1
	v_lshl_add_u32 v189, v19, 2, v14
	v_add_u32_e32 v19, 0x198, v8
	v_lshl_add_u32 v188, v20, 2, s46
	v_add_u32_e32 v20, v19, v1
	v_lshl_add_u32 v191, v19, 2, v14
	v_add_u32_e32 v19, 0x1dc, v8
	v_lshl_add_u32 v190, v20, 2, s46
	v_add_u32_e32 v20, v19, v1
	v_lshl_add_u32 v193, v19, 2, v14
	v_add_u32_e32 v19, 0x220, v8
	v_lshl_add_u32 v192, v20, 2, s46
	v_add_u32_e32 v20, v19, v1
	v_lshl_add_u32 v195, v19, 2, v14
	v_add_u32_e32 v19, 0x264, v8
	v_lshl_add_u32 v194, v20, 2, s46
	v_add_u32_e32 v20, v19, v1
	v_lshl_add_u32 v197, v19, 2, v14
	v_add_u32_e32 v19, 0x2a8, v8
	v_lshl_add_u32 v196, v20, 2, s46
	v_add_u32_e32 v20, v19, v1
	v_lshl_add_u32 v199, v19, 2, v14
	v_add_u32_e32 v19, 0x2ec, v8
	s_load_dwordx4 s[36:39], s[34:35], 0xd8
	v_lshl_add_u32 v198, v20, 2, s46
	v_add_u32_e32 v20, v19, v1
	v_lshl_add_u32 v201, v19, 2, v14
	v_add_u32_e32 v19, 0x330, v8
	v_add_u32_e32 v145, 0x400, v126
	v_ashrrev_i32_e32 v7, 2, v126
	v_add_u32_e32 v18, 0x600, v126
	v_lshl_add_u32 v179, v8, 2, v14
	v_lshl_add_u32 v200, v20, 2, s46
	v_add_u32_e32 v20, v19, v1
	v_lshl_add_u32 v203, v19, 2, v14
	v_add_u32_e32 v19, 0x374, v8
	v_add_u32_e32 v8, 0x3b8, v8
	v_and_b32_e32 v9, -4, v7
	v_and_b32_e32 v155, 48, v126
	v_ashrrev_i32_e32 v158, 4, v126
	v_ashrrev_i32_e32 v160, 4, v145
	v_ashrrev_i32_e32 v161, 4, v18
	v_cmp_lt_i32_e64 s[18:19], 3, v7
	v_cmp_lt_i32_e64 s[20:21], -1, v7
	v_or_b32_e32 v7, 3, v7
	v_ashrrev_i32_e32 v134, 3, v126
	v_lshl_add_u32 v202, v20, 2, s46
	v_add_u32_e32 v20, v19, v1
	v_lshl_add_u32 v205, v19, 2, v14
	v_add_u32_e32 v19, v8, v1
	s_movk_i32 s44, 0x1100
	v_lshlrev_b32_e32 v148, 3, v3
	v_add_u32_e32 v130, -3, v9
	v_lshl_add_u32 v11, v3, 4, s6
	v_add_u32_e32 v152, 0x7d, v9
	v_add_u32_e32 v12, s6, v155
	v_lshl_add_u32 v15, v153, 2, s45
	v_mul_lo_u32 v4, v158, s47
	v_mul_lo_u32 v16, v159, s47
	v_mul_lo_u32 v17, v160, s47
	v_mul_lo_u32 v18, v161, s47
	v_cmp_lt_i32_e64 s[22:23], -2, v9
	v_cmp_lt_i32_e64 s[24:25], -3, v9
	v_mul_lo_u32 v9, v9, s47
	v_mul_lo_u32 v7, v7, s47
	v_mul_u32_u24_e32 v3, 0x110, v3
	v_lshl_add_u32 v204, v20, 2, s46
	v_lshl_add_u32 v206, v19, 2, s46
	v_lshl_add_u32 v207, v8, 2, v14
	v_mul_lo_u32 v8, v144, s44
	v_mul_lo_u32 v5, v5, s47
	v_mul_lo_u32 v19, v134, s47
	v_mul_lo_u32 v20, v136, s47
	v_cmp_gt_i32_e64 s[4:5], 64, v126
	v_or_b32_e32 v149, 0x400, v148
	v_or_b32_e32 v150, 0x1000, v148
	v_ashrrev_i32_e32 v131, 31, v130
	v_add_u32_e32 v151, s64, v10
	v_cmp_lt_i32_e64 s[6:7], 0, v144
	v_cmp_eq_u32_e64 s[8:9], 7, v144
	v_ashrrev_i32_e32 v127, 31, v126
	v_cmp_gt_i32_e64 s[10:11], 64, v158
	v_cmp_gt_i32_e64 s[12:13], 64, v159
	v_cmp_gt_i32_e64 s[14:15], 64, v160
	v_cmp_gt_i32_e64 s[16:17], 64, v161
	v_ashrrev_i32_e32 v135, 31, v134
	v_ashrrev_i32_e32 v137, 31, v136
	v_lshl_add_u32 v208, v13, 1, v154
	v_add_u32_e32 v209, s40, v10
	v_add_u32_e32 v210, v6, v4
	v_add_u32_e32 v211, v6, v16
	v_add_u32_e32 v212, v6, v17
	v_add_u32_e32 v213, v6, v18
	s_mov_b64 s[44:45], 0x1000
	s_mov_b64 s[46:47], 0x2000
	s_mov_b64 s[48:49], 0x3000
	v_add_u32_e32 v214, v11, v9
	v_add_u32_e32 v215, v11, v7
	v_add_u32_e32 v216, v12, v3
	s_mov_b32 s65, 0xbecccccd
	v_mov_b32_e32 v217, 0x3c088889
	v_add_u32_e32 v218, v14, v8
	v_add_u32_e32 v219, v14, v5
	v_add_u32_e32 v220, v15, v19
	v_add_u32_e32 v221, v15, v20
	s_mov_b32 s66, s33
	s_branch .LBB0_3836

; #define SUB(k, bit) (!(kargs()->li == 1 && (k) == lo) || ((kargs()->submask >> (bit)) & 1u))
; __global__ void __launch_bounds__(NWAVES * 64, 2) fwd(Args args_unused) {
;     ...
;             if (SUB(pb + 5, 1)) {
; #pragma unroll
;                 for (int q = 0; q < 2; ++q) { const f32x4 ga_ = *(const f32x4*)(A->in[I_GSSM] + l * DM + q * 512 + 8 * lane), gb_ = *(const f32x4*)(A->in[I_GSSM] + l * DM + q * 512 + 8 * lane + 4);
;                     gnv[q][0] = ga_.x; gnv[q][1] = ga_.y; gnv[q][2] = ga_.z; gnv[q][3] = ga_.w; gnv[q][4] = gb_.x; gnv[q][5] = gb_.y; gnv[q][6] = gb_.z; gnv[q][7] = gb_.w; } }
;             if (SUB(pb + 5, 1))
;             for (int row0 = gw; row0 < M; row0 += 2 * NGW) {
;                 const int hh = lane >> 3;
;                 float l0[2], l1[2], l2[2]; v4u r0[2], r1[2], r2[2], yr[2][2], zr[2][2];
; #pragma unroll
;                 for (int k = 0; k < 2; ++k) { const int row = row0 + k * NGW;
;                     l0[k] = 0.f; l1[k] = 0.f; l2[k] = 0.f; r0[k] = (v4u){0u, 0u, 0u, 0u}; r1[k] = (v4u){0u, 0u, 0u, 0u}; r2[k] = (v4u){0u, 0u, 0u, 0u};
; #pragma unroll
;                     for (int q = 0; q < 2; ++q) { yr[k][q] = (v4u){0u, 0u, 0u, 0u}; zr[k][q] = (v4u){0u, 0u, 0u, 0u}; }
;                     if (row < M) {
;                         l0[k] = LSE[((size_t)0 * M + row) * 8 + hh]; l1[k] = LSE[((size_t)1 * M + row) * 8 + hh]; l2[k] = LSE[((size_t)2 * M + row) * 8 + hh];
;                         r0[k] = *(const v4u*)(OG + ((size_t)0 * M + row) * 512 + 8 * lane); r1[k] = *(const v4u*)(OG + ((size_t)1 * M + row) * 512 + 8 * lane); r2[k] = *(const v4u*)(OG + ((size_t)2 * M + row) * 512 + 8 * lane);
; #pragma unroll
;                         for (int q = 0; q < 2; ++q) { const int col = q * 512 + 8 * lane; yr[k][q] = *(const v4u*)(YS + (size_t)row * DM + col); zr[k][q] = *(const v4u*)ZP(Z, row, ZZB + col); } } }
.Lp8_post_1:
	s_cmp_eq_u32 s98, 1
	s_cbranch_scc1 .Lro_fin_1
	s_lshl_b32 s4, s33, 3
	s_add_i32 s4, s4, s62
	s_cmp_gt_i32 s4, 0x80ff
	s_cbranch_scc1 .LBB0_3954
	s_load_dwordx2 s[6:7], s[34:35], 0xc8
	v_lshlrev_b32_e32 v74, 5, v1
	v_mov_b32_e32 v75, 0
	s_mov_b64 s[8:9], 0x1000
	s_mov_b32 s5, 0x8100
	s_waitcnt lgkmcnt(0)
	v_lshl_add_u64 v[2:3], s[6:7], 0, v[74:75]
	v_lshl_add_u64 v[18:19], v[2:3], 0, s[8:9]
	v_add_co_u32_e32 v20, vcc, 0x1000, v2
	s_mov_b64 s[6:7], 0xb800000
	s_nop 0
	v_addc_co_u32_e32 v21, vcc, 0, v3, vcc
	global_load_dwordx4 v[2:5], v[18:19], off offset:16
	global_load_dwordx4 v[6:9], v[18:19], off offset:2048
	global_load_dwordx4 v[10:13], v[20:21], off
	global_load_dwordx4 v[14:17], v[18:19], off offset:2064
	v_lshrrev_b32_e32 v18, 1, v1
	v_and_b32_e32 v74, 28, v18
	v_lshl_add_u64 v[18:19], s[30:31], 0, v[74:75]
	v_lshlrev_b32_e32 v74, 4, v1
	v_lshl_add_u64 v[76:77], v[18:19], 0, s[6:7]
	v_lshl_add_u64 v[18:19], s[30:31], 0, v[74:75]
	s_mov_b64 s[6:7], 0x67c00000
	v_lshl_add_u64 v[78:79], v[18:19], 0, s[6:7]
	s_mov_b64 s[6:7], 0x75e00000
	v_lshl_add_u64 v[82:83], v[18:19], 0, s[6:7]
	s_mov_b64 s[6:7], 0x6dd00000
	v_and_b32_e32 v74, 0x1f0, v74
	v_lshrrev_b32_e32 v1, 5, v1
	v_mov_b32_e32 v20, 0x91200
	v_lshl_add_u64 v[86:87], v[18:19], 0, s[6:7]
	s_mov_b64 s[6:7], 0x5fb00000
	v_lshl_add_u64 v[80:81], s[26:27], 0, v[74:75]
	v_mad_u32_u24 v74, v1, s5, v20
	v_mov_b32_e32 v20, 0xa1400
	v_lshl_add_u64 v[88:89], v[18:19], 0, s[6:7]
	v_mbcnt_lo_u32_b32 v18, -1, 0
	s_lshl_b32 s12, s3, 3
	v_mad_u32_u24 v84, v1, s5, v20
	v_mov_b32_e32 v85, v75
	s_lshl_b32 s3, s3, 4
	v_mov_b32_e32 v1, 0x358637bd
	v_mbcnt_hi_u32_b32 v90, -1, v18
	s_branch .LBB0_3950
